# H tile rotation extended: second K-step LDS-DMA stage also issued before the previous tile's epilogue
# baseline (speedup 1.0000x reference)
.LBB0_1545:
	s_or_b64 exec, exec, s[16:17]
	s_waitcnt lgkmcnt(0)
	s_barrier
	s_waitcnt lgkmcnt(0)
	ds_read_b32 v0, v1 offset:184
	ds_read_b32 v2, v1 offset:188
	v_mov_b32_e32 v134, v201
	s_mov_b32 s0, 0x1ffff0
	s_waitcnt lgkmcnt(0)
	v_readfirstlane_b32 s6, v0
	v_lshlrev_b32_e32 v4, 4, v134
	v_and_b32_e32 v0, 32, v134
	v_readfirstlane_b32 s7, v2
	s_add_u32 s42, s6, 0xa80000
	v_bitop3_b32 v0, v4, v0, 48 bitop3:0x6c
	v_add_u32_e32 v4, 0x2000, v4
	s_addc_u32 s43, s7, 0
	v_bfe_u32 v5, v134, 2, 4
	v_and_or_b32 v6, v134, 64, v0
	v_lshrrev_b32_e32 v0, 3, v134
	v_lshrrev_b32_e32 v4, 7, v4
	s_add_u32 s44, s6, 0x13374000
	v_and_or_b32 v0, v0, s0, v5
	v_and_or_b32 v4, v4, s0, v5
	s_mul_i32 s0, s76, 22
	s_addc_u32 s45, s7, 0
	s_lshr_b32 s0, s0, 3
	v_readlane_b32 s1, v254, 23
	s_mul_hi_u32 s1, s0, s1
	s_mul_i32 s2, s1, s67
	s_sub_i32 s2, s0, s2
	s_add_i32 s3, s1, 1
	s_sub_i32 s4, s2, s67
	s_cmp_ge_u32 s2, s67
	s_cselect_b32 s1, s3, s1
	s_cselect_b32 s2, s4, s2
	s_add_i32 s3, s1, 1
	s_cmp_ge_u32 s2, s67
	s_cselect_b32 s54, s3, s1
	s_mul_i32 s55, s54, s67
	s_sub_i32 s1, s0, s55
	s_cmp_gt_i32 s1, 0
	v_readlane_b32 s2, v254, 25
	v_lshl_or_b32 v0, v0, 11, v6
	v_lshl_or_b32 v130, v4, 11, v6
	v_ashrrev_i32_e32 v4, 8, v134
	v_and_b32_e32 v5, 15, v134
	v_bfe_u32 v6, v134, 4, 2
	s_cselect_b64 s[8:9], -1, 0
	s_cmp_lt_u32 s2, s1
	v_readlane_b32 s1, v254, 14
	s_mul_i32 s58, s0, s1
	v_lshlrev_b32_e32 v7, 4, v6
	v_lshlrev_b32_e32 v8, 6, v5
	v_lshlrev_b32_e32 v9, 2, v134
	v_lshl_or_b32 v136, v4, 6, v5
	v_lshlrev_b32_e32 v5, 6, v134
	s_movk_i32 s12, 0x3c0
	v_ashrrev_i32_e32 v2, 6, v134
	s_cselect_b64 s[10:11], -1, 0
	s_add_i32 s58, s58, s2
	v_and_b32_e32 v9, 32, v9
	v_and_or_b32 v5, v5, s12, v7
	s_movk_i32 s12, 0x400
	v_and_b32_e32 v3, 3, v2
	v_xad_u32 v5, v5, v9, s12
	s_add_u32 s12, s6, 0x12b32000
	v_lshlrev_b32_e32 v135, 10, v2
	v_lshlrev_b32_e32 v2, 12, v3
	v_bitop3_b32 v8, v7, v9, v8 bitop3:0x36
	v_lshlrev_b32_e32 v137, 5, v3
	v_lshlrev_b32_e32 v3, 13, v4
	s_addc_u32 s13, s7, 0
	v_cmp_eq_u32_e64 s[2:3], 1, v4
	v_add_u32_e32 v10, s33, v8
	v_add_u32_e32 v11, s52, v8
	v_add_u32_e32 v12, s53, v8
	v_add_u32_e32 v13, s34, v8
	v_lshlrev_b32_e32 v138, 2, v6
	v_add_u32_e32 v4, 0x400, v8
	v_or_b32_e32 v6, 0x800, v3
	v_or_b32_e32 v7, 0x1000, v3
	v_or_b32_e32 v8, 0x1800, v3
	s_add_u32 s14, s6, 0x4e80000
	s_mov_b32 s56, 0
	v_cmp_lt_i32_e64 s[0:1], s49, v134
	v_cmp_gt_u32_e64 s[4:5], s47, v134
	v_mov_b32_e32 v131, v1
	s_addc_u32 s15, s7, 0
	v_add_u32_e32 v139, v10, v2
	v_add_u32_e32 v140, v4, v3
	v_add_u32_e32 v141, v5, v6
	v_add_u32_e32 v142, v5, v7
	v_add_u32_e32 v143, v5, v8
	v_add_u32_e32 v144, v11, v2
	v_add_u32_e32 v145, v12, v2
	v_add_u32_e32 v146, v13, v2
	s_mov_b32 s72, 0
	s_branch .LBB0_1548

.Lhr_1557:
	s_andn2_saveexec_b64 s[20:21], s[20:21]
	v_add_u32_e32 v236, s16, v134
	v_ashrrev_i32_e32 v237, 31, v236
	v_lshl_add_u64 v[236:237], v[236:237], 2, s[12:13]
	s_or_b64 exec, exec, s[20:21]
	global_load_dword v238, v[236:237], off
	s_lshl_b32 s17, s56, 12
	s_and_b32 s17, s17, 0x1000
	s_add_i32 s59, s17, 0x400
	s_ashr_i32 s19, s18, 31
	s_add_i32 s59, s59, 0x20000
	s_lshl_b64 s[20:21], s[18:19], 11
	s_add_u32 s26, s44, s20
	v_add_u32_e32 v240, s33, v135
	v_lshl_add_u32 v239, v134, 2, s59
	s_addc_u32 s27, s45, s21
	v_readfirstlane_b32 s17, v240
	v_add_u32_e32 v241, 0x2000, v240
	s_mov_b32 m0, s17
	v_readfirstlane_b32 s17, v241
	v_add_u32_e32 v242, 0x400, v135
	v_add_u32_e32 v243, 0x2000, v242
	v_add_u32_e32 v244, s52, v135
	v_add_u32_e32 v245, 0x2000, v244
	v_add_u32_e32 v246, 0x4000, v242
	v_add_u32_e32 v247, 0x6000, v242
	s_waitcnt lgkmcnt(0)
	v_lshl_add_u64 v[236:237], s[26:27], 0, v[0:1]
	global_load_lds_dwordx4 v[236:237], off
	s_mov_b32 m0, s17
	s_ashr_i32 s17, s16, 31
	s_lshl_b64 s[22:23], s[16:17], 11
	s_add_u32 s28, s42, s22
	s_addc_u32 s29, s43, s23
	s_or_b32 s24, s18, 0x80
	s_ashr_i32 s25, s24, 31
	s_lshl_b64 s[24:25], s[24:25], 11
	s_add_u32 s30, s44, s24
	v_lshl_add_u64 v[236:237], s[26:27], 0, v[130:131]
	v_readfirstlane_b32 s17, v242
	s_addc_u32 s31, s45, s25
	s_or_b32 s24, s16, 0x80
	global_load_lds_dwordx4 v[236:237], off
	v_lshl_add_u64 v[236:237], s[28:29], 0, v[0:1]
	s_mov_b32 m0, s17
	v_readfirstlane_b32 s17, v243
	s_ashr_i32 s25, s24, 31
	global_load_lds_dwordx4 v[236:237], off
	v_lshl_add_u64 v[236:237], s[28:29], 0, v[130:131]
	s_mov_b32 m0, s17
	v_readfirstlane_b32 s17, v244
	s_lshl_b64 s[24:25], s[24:25], 11
	global_load_lds_dwordx4 v[236:237], off
	v_lshl_add_u64 v[236:237], s[30:31], 0, v[0:1]
	s_mov_b32 m0, s17
	v_readfirstlane_b32 s17, v245
	s_add_u32 s24, s42, s24
	global_load_lds_dwordx4 v[236:237], off
	v_lshl_add_u64 v[236:237], s[30:31], 0, v[130:131]
	s_mov_b32 m0, s17
	s_addc_u32 s25, s43, s25
	v_readfirstlane_b32 s17, v246
	global_load_lds_dwordx4 v[236:237], off
	v_lshl_add_u64 v[236:237], s[24:25], 0, v[0:1]
	s_mov_b32 m0, s17
	v_readfirstlane_b32 s17, v247
	global_load_lds_dwordx4 v[236:237], off
	v_lshl_add_u64 v[236:237], s[24:25], 0, v[130:131]
	s_mov_b32 m0, s17
	s_nop 0
	global_load_lds_dwordx4 v[236:237], off
	s_add_u32 s26, s26, 0x80
	v_add_u32_e32 v228, s53, v135
	s_addc_u32 s27, s27, 0
	v_readfirstlane_b32 s17, v228
	v_lshl_add_u64 v[236:237], s[26:27], 0, v[0:1]
	s_mov_b32 m0, s17
	v_add_u32_e32 v229, 0x2000, v228
	global_load_lds_dwordx4 v[236:237], off
	v_lshl_add_u64 v[236:237], s[26:27], 0, v[130:131]
	v_readfirstlane_b32 s17, v229
	s_add_u32 s26, s28, 0x80
	v_add_u32_e32 v230, 0x8000, v242
	s_mov_b32 m0, s17
	s_addc_u32 s27, s29, 0
	v_readfirstlane_b32 s17, v230
	global_load_lds_dwordx4 v[236:237], off
	v_lshl_add_u64 v[236:237], s[26:27], 0, v[0:1]
	s_mov_b32 m0, s17
	v_add_u32_e32 v231, 0xa000, v242
	global_load_lds_dwordx4 v[236:237], off
	v_lshl_add_u64 v[236:237], s[26:27], 0, v[130:131]
	v_readfirstlane_b32 s17, v231
	s_add_u32 s26, s30, 0x80
	v_add_u32_e32 v232, s34, v135
	s_mov_b32 m0, s17
	s_addc_u32 s27, s31, 0
	v_readfirstlane_b32 s17, v232
	v_add_u32_e32 v233, 0x2000, v232
	global_load_lds_dwordx4 v[236:237], off
	v_lshl_add_u64 v[236:237], s[26:27], 0, v[0:1]
	s_mov_b32 m0, s17
	v_readfirstlane_b32 s17, v233
	global_load_lds_dwordx4 v[236:237], off
	v_lshl_add_u64 v[236:237], s[26:27], 0, v[130:131]
	s_mov_b32 m0, s17
	global_load_lds_dwordx4 v[236:237], off
	s_mov_b32 s72, 1
	s_branch .Lhr_cont

.LBB0_1561:
	s_or_b64 exec, exec, s[40:41]
	s_waitcnt vmcnt(4)
	s_barrier
	s_cmp_eq_u32 s72, 1
	s_cbranch_scc1 .Lhr_skip2
	s_add_u32 s26, s26, 0x80
	v_add_u32_e32 v153, s53, v135
	s_addc_u32 s27, s27, 0
	v_readfirstlane_b32 s17, v153
	v_lshl_add_u64 v[2:3], s[26:27], 0, v[0:1]
	s_mov_b32 m0, s17
	v_add_u32_e32 v154, 0x2000, v153
	global_load_lds_dwordx4 v[2:3], off
	v_lshl_add_u64 v[2:3], s[26:27], 0, v[130:131]
	v_readfirstlane_b32 s17, v154
	s_add_u32 s26, s28, 0x80
	v_add_u32_e32 v155, 0x8000, v147
	s_mov_b32 m0, s17
	s_addc_u32 s27, s29, 0
	v_readfirstlane_b32 s17, v155
	global_load_lds_dwordx4 v[2:3], off
	v_lshl_add_u64 v[2:3], s[26:27], 0, v[0:1]
	s_mov_b32 m0, s17
	v_add_u32_e32 v156, 0xa000, v147
	global_load_lds_dwordx4 v[2:3], off
	v_lshl_add_u64 v[2:3], s[26:27], 0, v[130:131]
	v_readfirstlane_b32 s17, v156
	s_add_u32 s26, s30, 0x80
	v_add_u32_e32 v157, s34, v135
	s_mov_b32 m0, s17
	s_addc_u32 s27, s31, 0
	v_readfirstlane_b32 s17, v157
	v_add_u32_e32 v158, 0x2000, v157
	global_load_lds_dwordx4 v[2:3], off
	v_lshl_add_u64 v[2:3], s[26:27], 0, v[0:1]
	s_mov_b32 m0, s17
	v_readfirstlane_b32 s17, v158
	global_load_lds_dwordx4 v[2:3], off
	v_lshl_add_u64 v[2:3], s[26:27], 0, v[130:131]
	s_mov_b32 m0, s17
	global_load_lds_dwordx4 v[2:3], off
	s_branch .Lhr_join2
.Lhr_skip2:
	v_add_u32_e32 v153, s53, v135
	v_add_u32_e32 v154, 0x2000, v153
	v_add_u32_e32 v155, 0x8000, v147
	v_add_u32_e32 v156, 0xa000, v147
	v_add_u32_e32 v157, s34, v135
	v_add_u32_e32 v158, 0x2000, v157
.Lhr_join2:
	s_mov_b32 s17, -2
	s_waitcnt vmcnt(6)
	v_mov_b32_e32 v2, 0
	s_mov_b64 s[26:27], s[6:7]
	v_mov_b32_e32 v3, v2
	v_mov_b32_e32 v4, v2
	v_mov_b32_e32 v5, v2
	v_mov_b32_e32 v6, v2
	v_mov_b32_e32 v7, v2
	v_mov_b32_e32 v8, v2
	v_mov_b32_e32 v9, v2
	v_mov_b32_e32 v10, v2
	v_mov_b32_e32 v11, v2
	v_mov_b32_e32 v12, v2
	v_mov_b32_e32 v13, v2
	v_mov_b32_e32 v14, v2
	v_mov_b32_e32 v15, v2
	v_mov_b32_e32 v16, v2
	v_mov_b32_e32 v17, v2
	v_mov_b32_e32 v18, v2
	v_mov_b32_e32 v19, v2
	v_mov_b32_e32 v20, v2
	v_mov_b32_e32 v21, v2
	v_mov_b32_e32 v22, v2
	v_mov_b32_e32 v23, v2
	v_mov_b32_e32 v24, v2
	v_mov_b32_e32 v25, v2
	v_mov_b32_e32 v26, v2
	v_mov_b32_e32 v27, v2
	v_mov_b32_e32 v28, v2
	v_mov_b32_e32 v29, v2
	v_mov_b32_e32 v30, v2
	v_mov_b32_e32 v31, v2
	v_mov_b32_e32 v32, v2
	v_mov_b32_e32 v33, v2
	v_mov_b32_e32 v34, v2
	v_mov_b32_e32 v35, v2
	v_mov_b32_e32 v36, v2
	v_mov_b32_e32 v37, v2
	v_mov_b32_e32 v38, v2
	v_mov_b32_e32 v39, v2
	v_mov_b32_e32 v40, v2
	v_mov_b32_e32 v41, v2
	v_mov_b32_e32 v42, v2
	v_mov_b32_e32 v43, v2
	v_mov_b32_e32 v44, v2
	v_mov_b32_e32 v45, v2
	v_mov_b32_e32 v46, v2
	v_mov_b32_e32 v47, v2
	v_mov_b32_e32 v48, v2
	v_mov_b32_e32 v49, v2
	v_mov_b32_e32 v50, v2
	v_mov_b32_e32 v51, v2
	v_mov_b32_e32 v52, v2
	v_mov_b32_e32 v53, v2
	v_mov_b32_e32 v54, v2
	v_mov_b32_e32 v55, v2
	v_mov_b32_e32 v56, v2
	v_mov_b32_e32 v57, v2
	v_mov_b32_e32 v58, v2
	v_mov_b32_e32 v59, v2
	v_mov_b32_e32 v60, v2
	v_mov_b32_e32 v61, v2
	v_mov_b32_e32 v62, v2
	v_mov_b32_e32 v63, v2
	v_mov_b32_e32 v64, v2
	v_mov_b32_e32 v65, v2
	v_mov_b32_e32 v66, v2
	v_mov_b32_e32 v67, v2
	v_mov_b32_e32 v68, v2
	v_mov_b32_e32 v69, v2
	v_mov_b32_e32 v70, v2
	v_mov_b32_e32 v71, v2
	v_mov_b32_e32 v72, v2
	v_mov_b32_e32 v73, v2
	v_mov_b32_e32 v74, v2
	v_mov_b32_e32 v75, v2
	v_mov_b32_e32 v76, v2
	v_mov_b32_e32 v77, v2
	v_mov_b32_e32 v78, v2
	v_mov_b32_e32 v79, v2
	v_mov_b32_e32 v80, v2
	v_mov_b32_e32 v81, v2
	v_mov_b32_e32 v82, v2
	v_mov_b32_e32 v83, v2
	v_mov_b32_e32 v84, v2
	v_mov_b32_e32 v85, v2
	v_mov_b32_e32 v86, v2
	v_mov_b32_e32 v87, v2
	v_mov_b32_e32 v88, v2
	v_mov_b32_e32 v89, v2
	v_mov_b32_e32 v90, v2
	v_mov_b32_e32 v91, v2
	v_mov_b32_e32 v92, v2
	v_mov_b32_e32 v93, v2
	v_mov_b32_e32 v94, v2
	v_mov_b32_e32 v95, v2
	v_mov_b32_e32 v96, v2
	v_mov_b32_e32 v97, v2
	v_mov_b32_e32 v98, v2
	v_mov_b32_e32 v99, v2
	v_mov_b32_e32 v100, v2
	v_mov_b32_e32 v101, v2
	v_mov_b32_e32 v102, v2
	v_mov_b32_e32 v103, v2
	v_mov_b32_e32 v104, v2
	v_mov_b32_e32 v105, v2
	v_mov_b32_e32 v106, v2
	v_mov_b32_e32 v107, v2
	v_mov_b32_e32 v108, v2
	v_mov_b32_e32 v109, v2
	v_mov_b32_e32 v110, v2
	v_mov_b32_e32 v111, v2
	v_mov_b32_e32 v112, v2
	v_mov_b32_e32 v113, v2
	v_mov_b32_e32 v114, v2
	v_mov_b32_e32 v115, v2
	v_mov_b32_e32 v116, v2
	v_mov_b32_e32 v117, v2
	v_mov_b32_e32 v118, v2
	v_mov_b32_e32 v119, v2
	v_mov_b32_e32 v120, v2
	v_mov_b32_e32 v121, v2
	v_mov_b32_e32 v122, v2
	v_mov_b32_e32 v123, v2
	v_mov_b32_e32 v124, v2
	v_mov_b32_e32 v125, v2
	v_mov_b32_e32 v126, v2
	v_mov_b32_e32 v127, v2
	v_mov_b32_e32 v128, v2
	v_mov_b32_e32 v129, v2
	s_barrier
